# v34 + SW attention stage 1 load de-serialisation: V rows and K-rope rows issued together with the K rows (one latency instead of three)
# speedup vs baseline: 1.0021x; 1.0021x over previous
; __device__ __forceinline__ void sw_attn(const bf16* QKV, const float* rope, const float* qg, const float* kg, const float* sinks, bf16* O, LAS unsigned char* lds, int tid) {
;     ...
;     for (int u = blockIdx.x; u < 512; u += gridDim.x) {
;         const int blk = u & 31, kvh = (u >> 5) & 1, b = u >> 6;
;         const size_t tok0 = (size_t)b * SEQ;
;         __syncthreads();
;         v4u qraw[4]; f32x4 rraw[4];
;     ...
;         SW_LOADQ(0);
;         {
;             const int row = tid >> 1, half = tid & 1, kpos = blk * 128 - 128 + row;
;             v4u outw[4];
;             if (kpos >= 0) {
;                 const bf16* kp = QKV + ((size_t)(b * 20 + 16 + kvh) * SEQ + kpos) * 64 + 32 * half;
;     ...
;             const int vdc = tid & 7, vkg = tid >> 3, kpos0 = blk * 128 - 128 + 4 * vkg;
;             v4u vreg[4];
; #pragma unroll
;             for (int i = 0; i < 4; ++i) vreg[i] = kpos0 >= 0 ? *(const v4u*)(QKV + ((size_t)(b * 20 + 18 + kvh) * SEQ + kpos0 + i) * 64 + 8 * vdc) : (v4u){0u, 0u, 0u, 0u};
.LBB0_159:
	s_bfe_u32 s20, s29, 0x10005
	s_ashr_i32 s10, s29, 6
	s_lshl_b32 s30, s20, 3
	s_mul_i32 s21, s10, 20
	s_ashr_i32 s11, s10, 31
	s_add_i32 s31, s30, s21
	s_and_b32 s16, s29, 31
	s_lshl_b64 s[12:13], s[10:11], 12
	s_add_i32 s10, s31, s28
	s_lshl_b32 s18, s16, 7
	s_ashr_i32 s11, s10, 31
	s_or_b32 s17, s12, s18
	s_lshl_b64 s[10:11], s[10:11], 12
	v_mov_b32_e32 v1, s13
	v_or_b32_e32 v0, s17, v118
	v_mov_b32_e32 v3, s11
	v_or_b32_e32 v2, s10, v118
	v_readlane_b32 s10, v253, 2
	v_or_b32_e32 v2, s18, v2
	v_lshlrev_b64 v[0:1], 6, v[0:1]
	v_readlane_b32 s11, v253, 3
	v_lshlrev_b64 v[2:3], 7, v[2:3]
	s_waitcnt lgkmcnt(0)
	v_lshl_add_u64 v[124:125], s[10:11], 0, v[0:1]
	s_barrier
	v_lshl_add_u64 v[16:17], v[112:113], 0, v[2:3]
	global_load_dwordx4 v[12:15], v[124:125], off offset:48
	global_load_dwordx4 v[8:11], v[124:125], off offset:32
	global_load_dwordx4 v[0:3], v[124:125], off offset:16
	global_load_dwordx4 v[4:7], v[124:125], off
	global_load_dwordx4 v[80:83], v[16:17], off
	global_load_dwordx4 v[84:87], v[16:17], off offset:32
	global_load_dwordx4 v[88:91], v[16:17], off offset:64
	global_load_dwordx4 v[92:95], v[16:17], off offset:96
	s_lshr_b32 s14, s99, 2
	s_add_i32 s14, s14, s30
	s_ashr_i32 s15, s14, 31
	s_lshl_b64 s[14:15], s[14:15], 2
	s_add_u32 s14, s27, s14
	s_addc_u32 s15, s88, s15
	v_mbcnt_lo_u32_b32 v237, -1, 0
	v_mbcnt_hi_u32_b32 v237, -1, v237
	v_and_b32_e32 v237, 3, v237
	v_lshlrev_b32_e32 v237, 3, v237
	global_load_dword v236, v237, s[14:15]
	s_add_i32 s34, s18, 0xffffff80
	v_add_u32_e32 v156, s34, v119
	s_mov_b32 s19, s13
	s_add_i32 s14, s21, s20
	s_add_i32 s14, s14, 18
	s_ashr_i32 s15, s14, 31
	s_lshl_b64 s[14:15], s[14:15], 12
	v_add_u32_e32 v242, s34, v130
	v_mov_b32_e32 v243, 0
	v_lshl_add_u64 v[240:241], s[14:15], 0, v[242:243]
	v_lshlrev_b64 v[240:241], 7, v[240:241]
	v_lshl_add_u64 v[240:241], v[114:115], 0, v[240:241]
	v_cmp_lt_i32_e32 vcc, -1, v242
	v_mov_b32_e32 v214, 0
	v_mov_b32_e32 v215, 0
	v_mov_b32_e32 v216, 0
	v_mov_b32_e32 v217, 0
	v_mov_b32_e32 v218, 0
	v_mov_b32_e32 v219, 0
	v_mov_b32_e32 v220, 0
	v_mov_b32_e32 v221, 0
	v_mov_b32_e32 v222, 0
	v_mov_b32_e32 v223, 0
	v_mov_b32_e32 v224, 0
	v_mov_b32_e32 v225, 0
	v_mov_b32_e32 v226, 0
	v_mov_b32_e32 v227, 0
	v_mov_b32_e32 v228, 0
	v_mov_b32_e32 v229, 0
	s_and_saveexec_b64 s[10:11], vcc
	global_load_dwordx4 v[214:217], v[240:241], off
	global_load_dwordx4 v[218:221], v[240:241], off offset:128
	global_load_dwordx4 v[222:225], v[240:241], off offset:256
	global_load_dwordx4 v[226:229], v[240:241], off offset:384
	s_or_b64 exec, exec, s[10:11]
	v_cmp_lt_i32_e32 vcc, -1, v156
	v_mov_b32_e32 v19, 0
	v_mov_b32_e32 v18, 0
	v_mov_b32_e32 v17, 0
	v_mov_b32_e32 v16, 0
	v_mov_b32_e32 v23, 0
	v_mov_b32_e32 v22, 0
	v_mov_b32_e32 v21, 0
	v_mov_b32_e32 v20, 0
	v_mov_b32_e32 v27, 0
	v_mov_b32_e32 v26, 0
	v_mov_b32_e32 v25, 0
	v_mov_b32_e32 v24, 0
	v_mov_b32_e32 v31, 0
	v_mov_b32_e32 v30, 0
	v_mov_b32_e32 v29, 0
	v_mov_b32_e32 v28, 0
	s_and_saveexec_b64 s[10:11], vcc
	s_cbranch_execz .LBB0_163
	s_add_i32 s14, s21, s20
	s_add_i32 s14, s14, 16
	s_ashr_i32 s15, s14, 31
	s_lshl_b64 s[14:15], s[14:15], 19
	s_add_u32 s14, s90, s14
	s_addc_u32 s15, s91, s15
	v_lshlrev_b64 v[16:17], 7, v[156:157]
	v_lshl_add_u64 v[16:17], s[14:15], 0, v[16:17]
	v_mov_b32_e32 v123, v157
	v_lshl_add_u64 v[16:17], v[16:17], 0, v[122:123]
	global_load_dwordx4 v[32:35], v[16:17], off offset:48
	global_load_dwordx4 v[36:39], v[16:17], off offset:32
	global_load_dwordx4 v[56:59], v[16:17], off offset:16
	global_load_dwordx4 v[46:49], v[16:17], off
	v_lshl_add_u64 v[240:241], s[12:13], 0, v[156:157]
	v_readlane_b32 s12, v253, 2
	v_lshlrev_b64 v[240:241], 6, v[240:241]
	v_readlane_b32 s13, v253, 3
	s_nop 1
	v_lshl_add_u64 v[240:241], s[12:13], 0, v[240:241]
	global_load_dwordx4 v[198:201], v[240:241], off offset:48
	global_load_dwordx4 v[202:205], v[240:241], off offset:16
	global_load_dwordx4 v[206:209], v[240:241], off offset:32
	global_load_dwordx4 v[210:213], v[240:241], off
	ds_read_b128 v[28:31], v129
	ds_read_b128 v[24:27], v129 offset:16
	ds_read_b128 v[20:23], v129 offset:32
	ds_read_b128 v[16:19], v129 offset:48
	s_waitcnt vmcnt(0)
	ds_read_b128 v[62:65], v129 offset:64
	ds_read_b128 v[68:71], v129 offset:80
	s_waitcnt lgkmcnt(4)
	v_mov_b32_e32 v43, v27
	ds_read_b128 v[72:75], v129 offset:96
	s_waitcnt lgkmcnt(3)
	v_mov_b32_e32 v42, v19
	s_waitcnt lgkmcnt(2)
	v_mov_b32_e32 v19, v62
	v_mov_b32_e32 v60, v63
	v_mov_b32_e32 v61, v64
	s_waitcnt lgkmcnt(1)
	v_pk_mov_b32 v[66:67], v[64:65], v[68:69] op_sel:[1,0]
	v_mov_b32_e32 v68, v69
	v_mov_b32_e32 v69, v70
	s_waitcnt vmcnt(3)
	v_lshlrev_b32_e32 v77, 16, v32
	s_waitcnt vmcnt(2)
	v_and_b32_e32 v62, 0xffff0000, v37
	s_waitcnt vmcnt(1)
	v_lshlrev_b32_e32 v44, 16, v56
	s_waitcnt vmcnt(0)
; __device__ __forceinline__ float shx(float v, int lane, int m) { return __builtin_bit_cast(float, __builtin_amdgcn_ds_bpermute((lane ^ m) << 2, __builtin_bit_cast(int, v))); }
; #define LAS __attribute__((address_space(3)))
; __device__ __forceinline__ void unpack8(const v4u w, float* v) { v[0] = bf_lo(w.x); v[1] = bf_hi(w.x); v[2] = bf_lo(w.y); v[3] = bf_hi(w.y); v[4] = bf_lo(w.z); v[5] = bf_hi(w.z); v[6] = bf_lo(w.w); v[7] = bf_hi(w.w); }
; __device__ __forceinline__ void sw_attn(const bf16* QKV, const float* rope, const float* qg, const float* kg, const float* sinks, bf16* O, LAS unsigned char* lds, int tid) {
;     ...
;                 float v[32];
; #pragma unroll
;                 for (int c = 0; c < 4; ++c) unpack8(*(const v4u*)(kp + 8 * c), v + 8 * c);
;                 float ss = 0.f;
; #pragma unroll
;                 for (int d = 0; d < 32; ++d) ss = fmaf(v[d], v[d], ss);
;                 ss += pg8::shx(ss, lane, 1);
;                 const float rs = __builtin_amdgcn_rsqf(ss * (1.0f / 64.0f) + 1e-6f);
; #pragma unroll
;                 for (int d4 = 0; d4 < 8; ++d4) { const f32x4 g4 = *(const LAS f32x4*)(gtab + 64 + 32 * half + 4 * d4); v[4 * d4] *= rs * g4[0]; v[4 * d4 + 1] *= rs * g4[1]; v[4 * d4 + 2] *= rs * g4[2]; v[4 * d4 + 3] *= rs * g4[3]; }
;                 if (half == 0) { const f32x4* rp4 = (const f32x4*)(rope + (tok0 + kpos) * 16); const f32x4 c0 = rp4[0], c1 = rp4[1], s0 = rp4[2], s1 = rp4[3];
; #pragma unroll
;                     for (int i = 0; i < 8; ++i) { const float c = i < 4 ? c0[i & 3] : c1[i & 3], sn = i < 4 ? s0[i & 3] : s1[i & 3], x1 = v[i], x2 = v[8 + i]; v[i] = x1 * c - x2 * sn; v[8 + i] = x2 * c + x1 * sn; } }
	v_lshlrev_b32_e32 v50, 16, v46
	v_and_b32_e32 v51, 0xffff0000, v46
	v_fma_f32 v27, v50, v50, 0
	v_fmac_f32_e32 v27, v51, v51
	v_lshlrev_b32_e32 v52, 16, v47
	v_and_b32_e32 v53, 0xffff0000, v47
	v_fmac_f32_e32 v27, v52, v52
	v_fmac_f32_e32 v27, v53, v53
	v_lshlrev_b32_e32 v54, 16, v48
	v_and_b32_e32 v55, 0xffff0000, v48
	v_fmac_f32_e32 v27, v54, v54
	v_lshlrev_b32_e32 v102, 16, v49
	v_fmac_f32_e32 v27, v55, v55
	v_and_b32_e32 v41, 0xffff0000, v49
	v_fmac_f32_e32 v27, v102, v102
	v_fmac_f32_e32 v27, v41, v41
	v_and_b32_e32 v45, 0xffff0000, v56
	v_fmac_f32_e32 v27, v44, v44
	v_lshlrev_b32_e32 v46, 16, v57
	v_fmac_f32_e32 v27, v45, v45
	v_and_b32_e32 v47, 0xffff0000, v57
	v_fmac_f32_e32 v27, v46, v46
	v_lshlrev_b32_e32 v48, 16, v58
	v_fmac_f32_e32 v27, v47, v47
	v_and_b32_e32 v49, 0xffff0000, v58
	v_fmac_f32_e32 v27, v48, v48
	v_fmac_f32_e32 v27, v49, v49
	v_lshlrev_b32_e32 v56, 16, v59
	v_and_b32_e32 v40, 0xffff0000, v59
	v_fmac_f32_e32 v27, v56, v56
	v_lshlrev_b32_e32 v57, 16, v36
	v_fmac_f32_e32 v27, v40, v40
	v_fmac_f32_e32 v27, v57, v57
	v_and_b32_e32 v58, 0xffff0000, v36
	v_lshlrev_b32_e32 v59, 16, v37
	v_fmac_f32_e32 v27, v58, v58
	v_fmac_f32_e32 v27, v59, v59
	v_lshlrev_b32_e32 v63, 16, v38
	v_fmac_f32_e32 v27, v62, v62
	v_fmac_f32_e32 v27, v63, v63
	v_and_b32_e32 v64, 0xffff0000, v38
	v_lshlrev_b32_e32 v65, 16, v39
	v_fmac_f32_e32 v27, v64, v64
	v_fmac_f32_e32 v27, v65, v65
	v_and_b32_e32 v76, 0xffff0000, v39
	v_fmac_f32_e32 v27, v76, v76
	ds_read_b128 v[36:39], v129 offset:112
	v_fmac_f32_e32 v27, v77, v77
	v_and_b32_e32 v78, 0xffff0000, v32
	v_lshlrev_b32_e32 v79, 16, v33
	v_fmac_f32_e32 v27, v78, v78
	v_fmac_f32_e32 v27, v79, v79
	v_and_b32_e32 v104, 0xffff0000, v33
	v_lshlrev_b32_e32 v105, 16, v34
	v_fmac_f32_e32 v27, v104, v104
	s_waitcnt lgkmcnt(1)
	v_mov_b32_e32 v99, v74
	v_fmac_f32_e32 v27, v105, v105
	s_waitcnt lgkmcnt(0)
	v_pk_mov_b32 v[106:107], v[74:75], v[36:37] op_sel:[1,0]
	v_and_b32_e32 v74, 0xffff0000, v34
	v_lshlrev_b32_e32 v75, 16, v35
	v_fmac_f32_e32 v27, v74, v74
	v_and_b32_e32 v101, 0xffff0000, v35
	v_fmac_f32_e32 v27, v75, v75
	v_fmac_f32_e32 v27, v101, v101
	ds_bpermute_b32 v32, v121, v27
	v_pk_mov_b32 v[96:97], v[70:71], v[72:73] op_sel:[1,0]
	v_mov_b32_e32 v98, v73
	s_waitcnt lgkmcnt(0)
	v_add_f32_e32 v27, v27, v32
	v_fmamk_f32 v27, v27, 0x3c800000, v232
	v_rsq_f32_e32 v100, v27
	s_nop 0
	v_pk_mul_f32 v[28:29], v[28:29], v[100:101] op_sel_hi:[1,0]
	s_nop 0
	v_pk_mul_f32 v[72:73], v[28:29], v[50:51]
	v_pk_mul_f32 v[28:29], v[30:31], v[100:101] op_sel_hi:[1,0]
	v_pk_mul_f32 v[24:25], v[24:25], v[100:101] op_sel_hi:[1,0]
	v_pk_mul_f32 v[70:71], v[28:29], v[52:53]
	v_pk_mul_f32 v[52:53], v[24:25], v[54:55]
	v_mul_f32_e32 v24, v26, v100
	v_pk_mul_f32 v[26:27], v[42:43], v[100:101] op_sel_hi:[1,0]
	v_pk_mul_f32 v[16:17], v[16:17], v[100:101] op_sel_hi:[1,0]
	v_pk_mul_f32 v[50:51], v[26:27], v[40:41]
	v_pk_mul_f32 v[26:27], v[16:17], v[48:49]
	v_pk_mul_f32 v[16:17], v[18:19], v[100:101] op_sel_hi:[1,0]
	v_pk_mul_f32 v[20:21], v[20:21], v[100:101] op_sel_hi:[1,0]
	v_pk_mul_f32 v[28:29], v[16:17], v[56:57]
	v_pk_mul_f32 v[16:17], v[60:61], v[100:101] op_sel_hi:[1,0]
	v_pk_mul_f32 v[20:21], v[20:21], v[44:45]
	v_pk_mul_f32 v[30:31], v[16:17], v[58:59]
	v_pk_mul_f32 v[16:17], v[66:67], v[100:101] op_sel_hi:[1,0]
	v_pk_mul_f32 v[22:23], v[22:23], v[100:101] op_sel_hi:[1,0]
	v_pk_mul_f32 v[32:33], v[16:17], v[62:63]
	v_pk_mul_f32 v[16:17], v[68:69], v[100:101] op_sel_hi:[1,0]
	v_mul_f32_e32 v24, v24, v102
	v_pk_mul_f32 v[34:35], v[16:17], v[64:65]
	v_pk_mul_f32 v[16:17], v[96:97], v[100:101] op_sel_hi:[1,0]
	v_pk_mul_f32 v[22:23], v[22:23], v[46:47]
	v_pk_mul_f32 v[40:41], v[16:17], v[76:77]
	v_pk_mul_f32 v[16:17], v[98:99], v[100:101] op_sel_hi:[1,0]
	s_nop 0
	v_pk_mul_f32 v[42:43], v[16:17], v[78:79]
	v_pk_mul_f32 v[16:17], v[106:107], v[100:101] op_sel_hi:[1,0]
	s_nop 0
	v_pk_mul_f32 v[44:45], v[16:17], v[104:105]
	v_mov_b32_e32 v16, v37
	v_mov_b32_e32 v17, v38
	v_pk_mul_f32 v[16:17], v[16:17], v[100:101] op_sel_hi:[1,0]
	s_nop 0
	v_pk_mul_f32 v[36:37], v[16:17], v[74:75]
	v_mul_f32_e32 v16, v39, v100
	v_mul_f32_e32 v38, v16, v101
	s_mov_b64 s[14:15], exec
	v_readlane_b32 vcc_lo, v252, 0
	v_readlane_b32 vcc_hi, v252, 1
	s_and_b64 vcc, s[14:15], vcc
	s_mov_b64 exec, vcc
	s_cbranch_execz .LBB0_162
	v_mov_b32_e32 v25, v51
	s_waitcnt vmcnt(0)
	v_pk_mul_f32 v[62:63], v[20:21], v[206:207]
	v_pk_mul_f32 v[54:55], v[72:73], v[206:207]
	s_waitcnt vmcnt(0)
	v_pk_fma_f32 v[62:63], v[72:73], v[210:211], v[62:63] neg_lo:[0,0,1] neg_hi:[0,0,1]
	v_pk_fma_f32 v[20:21], v[20:21], v[210:211], v[54:55]
	v_pk_mul_f32 v[54:55], v[22:23], v[208:209]
	v_pk_mul_f32 v[56:57], v[70:71], v[208:209]
	v_pk_fma_f32 v[54:55], v[70:71], v[212:213], v[54:55] neg_lo:[0,0,1] neg_hi:[0,0,1]
	v_pk_fma_f32 v[22:23], v[22:23], v[212:213], v[56:57]
	v_pk_mul_f32 v[56:57], v[26:27], v[198:199]
	v_pk_mul_f32 v[16:17], v[52:53], v[198:199]
	v_pk_fma_f32 v[56:57], v[52:53], v[202:203], v[56:57] neg_lo:[0,0,1] neg_hi:[0,0,1]
	v_mov_b32_e32 v52, v28
	v_mov_b32_e32 v53, v50
	v_pk_fma_f32 v[26:27], v[26:27], v[202:203], v[16:17]
	v_mul_f32_e32 v46, v24, v200
	v_pk_mul_f32 v[52:53], v[52:53], v[200:201]
	v_mov_b32_e32 v18, v205
	v_mov_b32_e32 v19, v201
	v_pk_mul_f32 v[18:19], v[50:51], v[18:19]
	v_mul_f32_e32 v16, v28, v204
	v_mov_b32_e32 v17, v18
	v_mov_b32_e32 v47, v19
	v_pk_fma_f32 v[24:25], v[24:25], v[204:205], v[52:53] neg_lo:[0,0,1] neg_hi:[0,0,1]
	v_pk_add_f32 v[16:17], v[16:17], v[46:47]
	v_mov_b32_e32 v72, v62
	v_mov_b32_e32 v73, v63
	v_mov_b32_e32 v70, v54
	v_mov_b32_e32 v71, v55
	v_mov_b32_e32 v52, v56
	v_mov_b32_e32 v53, v57
	v_mov_b32_e32 v51, v25
	v_mov_b32_e32 v28, v16
	v_mov_b32_e32 v50, v17

; #define LAS __attribute__((address_space(3)))
; __device__ __forceinline__ void sw_attn(const bf16* QKV, const float* rope, const float* qg, const float* kg, const float* sinks, bf16* O, LAS unsigned char* lds, int tid) {
;     ...
;             for (int c = 0; c < 4; ++c) *(LAS v4u*)(kl + row * KROW + 64 * half + 16 * c) = outw[c];
;     ...
; #pragma unroll
;             for (int i = 0; i < 4; ++i) vreg[i] = kpos0 >= 0 ? *(const v4u*)(QKV + ((size_t)(b * 20 + 18 + kvh) * SEQ + kpos0 + i) * 64 + 8 * vdc) : (v4u){0u, 0u, 0u, 0u};
; #pragma unroll
;             for (int j = 0; j < 4; ++j) {
;                 const unsigned w0 = vreg[0][j], w1 = vreg[1][j], w2 = vreg[2][j], w3 = vreg[3][j];
;                 const u32x2 e = {(w0 & 0xffffu) | (w1 << 16), (w2 & 0xffffu) | (w3 << 16)};
;                 const u32x2 o = {(w0 >> 16) | (w1 & 0xffff0000u), (w2 >> 16) | (w3 & 0xffff0000u)};
;                 *(LAS u32x2*)(vl + (8 * vdc + 2 * j) * VROW + 8 * vkg) = e; *(LAS u32x2*)(vl + (8 * vdc + 2 * j + 1) * VROW + 8 * vkg) = o;
;             }
;         }
;         __syncthreads();
.LBB0_163:
	s_or_b64 exec, exec, s[10:11]
	ds_write_b128 v132, v[16:19]
	ds_write_b128 v132, v[20:23] offset:16
	ds_write_b128 v132, v[24:27] offset:32
	ds_write_b128 v132, v[28:31] offset:48
	s_waitcnt vmcnt(0)
	v_add_u32_e32 v244, 0x9000, v133
	v_add_u32_e32 v245, 0x9800, v133
	v_and_b32_e32 v32, 0xffff, v214
	v_lshl_or_b32 v32, v218, 16, v32
	v_and_b32_e32 v33, 0xffff, v222
	v_lshl_or_b32 v33, v226, 16, v33
	v_lshrrev_b32_e32 v34, 16, v214
	v_and_or_b32 v34, v218, s37, v34
	v_lshrrev_b32_e32 v35, 16, v222
	v_and_or_b32 v35, v226, s37, v35
	ds_write2_b64 v244, v[32:33], v[34:35] offset1:65
	v_and_b32_e32 v32, 0xffff, v215
	v_lshl_or_b32 v32, v219, 16, v32
	v_and_b32_e32 v33, 0xffff, v223
	v_lshl_or_b32 v33, v227, 16, v33
	v_lshrrev_b32_e32 v34, 16, v215
	v_and_or_b32 v34, v219, s37, v34
	v_lshrrev_b32_e32 v35, 16, v223
	v_and_or_b32 v35, v227, s37, v35
	ds_write2_b64 v244, v[32:33], v[34:35] offset0:130 offset1:195
	v_and_b32_e32 v32, 0xffff, v216
	v_lshl_or_b32 v32, v220, 16, v32
	v_and_b32_e32 v33, 0xffff, v224
	v_lshl_or_b32 v33, v228, 16, v33
	v_lshrrev_b32_e32 v34, 16, v216
	v_and_or_b32 v34, v220, s37, v34
	v_lshrrev_b32_e32 v35, 16, v224
	v_and_or_b32 v35, v228, s37, v35
	ds_write2_b64 v245, v[32:33], v[34:35] offset0:4 offset1:69
	v_and_b32_e32 v32, 0xffff, v217
	v_lshl_or_b32 v32, v221, 16, v32
	v_and_b32_e32 v33, 0xffff, v225
	v_lshl_or_b32 v33, v229, 16, v33
	v_lshrrev_b32_e32 v34, 16, v217
	v_and_or_b32 v34, v221, s37, v34
	v_lshrrev_b32_e32 v35, 16, v225
	v_and_or_b32 v35, v229, s37, v35
	ds_write2_b64 v245, v[32:33], v[34:35] offset0:134 offset1:199
	v_mov_b32_e32 v17, s19
	v_or_b32_e32 v16, s17, v120
	s_cmp_lg_u32 s16, 0
	s_cselect_b64 s[10:11], -1, 0
	v_lshlrev_b64 v[16:17], 11, v[16:17]
	v_mov_b64_e32 v[98:99], v[6:7]
	v_mov_b64_e32 v[102:103], v[2:3]
	v_mov_b64_e32 v[106:107], v[10:11]
	v_mov_b64_e32 v[110:111], v[14:15]
	s_mov_b32 s34, 0
	v_lshl_add_u64 v[126:127], v[116:117], 0, v[16:17]
	s_or_b64 s[12:13], s[10:11], s[38:39]
	s_or_b64 s[14:15], s[10:11], s[6:7]
	s_nor_b64 s[16:17], s[10:11], s[8:9]
	v_or_b32_e32 v128, s18, v118
	v_mov_b64_e32 v[96:97], v[4:5]
	v_mov_b64_e32 v[100:101], v[0:1]
	v_mov_b64_e32 v[104:105], v[8:9]
	v_mov_b64_e32 v[108:109], v[12:13]
	s_waitcnt lgkmcnt(0)
	s_barrier
	s_branch .LBB0_174
